# scan: software-pipelined chunk loop (stage(m-1) then operand prep(m) in one barrier interval, double-buffered operand/YI/YK LDS sets), output store moved to idle waves 4,5
# speedup vs baseline: 1.6838x; 1.6838x over previous
.LBB0_391:
	s_andn2_b64 vcc, exec, s[0:1]
	s_cbranch_vccnz .LBB0_471
	v_readlane_b32 s0, v252, 25
	v_mov_b32_e32 v115, v228
	v_readlane_b32 s1, v252, 26
	s_andn2_b64 vcc, exec, s[0:1]
	v_readfirstlane_b32 s0, v115
	s_cbranch_vccnz .LBB0_416
	s_ashr_i32 s2, s0, 6
	v_bfe_u32 v7, v115, 4, 2
	v_lshl_or_b32 v130, s2, 2, v7
	s_cmp_lt_i32 s2, 4
	v_cmp_lt_i32_e32 vcc, s33, v130
	s_cselect_b64 s[40:41], -1, 0
	s_lshl_b32 s3, s2, 4
	v_cndmask_b32_e32 v7, v207, v208, vcc
	s_cmp_lt_i32 s2, 2
	v_sub_u32_e32 v131, v7, v130
	v_bfe_u32 v7, v115, 3, 3
	s_cselect_b64 s[14:15], -1, 0
	s_cmp_gt_i32 s2, 1
	v_and_b32_e32 v4, 31, v115
	s_mul_i32 s26, s2, 0x410
	v_lshl_or_b32 v132, s2, 3, v7
	s_mul_i32 s6, s2, 0x420
	s_cselect_b64 s[12:13], -1, 0
	s_lshr_b32 s100, s2, 1
	s_cmp_eq_u32 s100, 2
	s_cselect_b32 s100, 1, 0
	s_and_b32 s7, s2, 3
	s_lshl_b32 s8, s7, 5
	s_lshl_b32 s7, s7, 12
	s_add_i32 s10, s2, -2
	s_lshl_b32 s2, s2, 11
	v_ashrrev_i32_e32 v1, 2, v115
	v_and_b32_e32 v0, 63, v115
	v_lshlrev_b32_e32 v11, 6, v4
	s_add_i32 s2, s2, 0x10400
	v_lshlrev_b32_e32 v128, 1, v1
	v_lshl_or_b32 v129, v0, 2, v206
	v_and_b32_e32 v0, 0x7ffffff0, v1
	v_cmp_lt_i32_e32 vcc, s33, v132
	v_lshlrev_b32_e32 v138, 8, v4
	v_add_u32_e32 v140, s2, v11
	s_movk_i32 s2, 0xff40
	v_and_or_b32 v5, v128, 8, v0
	v_and_b32_e32 v6, 3, v115
	v_cndmask_b32_e32 v7, v207, v208, vcc
	v_mad_i32_i24 v142, v4, s2, v138
	s_movk_i32 s2, 0x11ff
	v_sub_u32_e32 v133, v7, v132
	v_lshlrev_b32_e32 v7, 3, v6
	v_lshrrev_b32_e32 v5, 3, v5
	v_bitop3_b32 v144, v4, s2, v209 bitop3:0x36
	s_movk_i32 s2, 0x820
	v_cmp_eq_u32_e64 s[0:1], 0, v6
	v_cmp_lt_u32_e64 s[38:39], 1, v6
	v_and_b32_e32 v8, 8, v1
	v_mul_u32_u24_e32 v137, 0x420, v6
	s_lshl_b32 s11, s10, 11
	v_mad_u32_u24 v145, v6, s2, v128
	v_lshlrev_b32_e32 v6, 11, v6
	v_bitop3_b32 v21, v5, v7, 8 bitop3:0x78
	v_and_or_b32 v8, v128, 6, v8
	s_add_i32 s11, s11, 0x10400
	v_or_b32_e32 v14, 4, v7
	v_lshl_add_u32 v6, v21, 4, v6
	v_bfe_u32 v3, v115, 5, 1
	v_add_u32_e32 v12, s11, v11
	v_lshrrev_b32_e32 v15, 2, v14
	s_movk_i32 s2, 0x410
	v_or_b32_e32 v147, v6, v8
	v_or_b32_e32 v6, 1, v7
	v_lshl_or_b32 v139, v3, 3, v12
	v_or_b32_e32 v11, 2, v7
	v_or_b32_e32 v12, 3, v7
	v_mad_u32_u24 v146, v15, s2, v128
	v_or_b32_e32 v15, 5, v7
	v_or_b32_e32 v17, 6, v7
	v_or_b32_e32 v19, 7, v7
	v_lshlrev_b32_e32 v7, 8, v6
	v_bitop3_b32 v6, v5, v6, 9 bitop3:0x78
	v_lshl_add_u32 v6, v6, 4, v7
	v_or_b32_e32 v148, v6, v8
	v_lshlrev_b32_e32 v6, 8, v11
	v_bitop3_b32 v7, v5, v11, 10 bitop3:0x78
	v_lshl_add_u32 v6, v7, 4, v6
	v_or_b32_e32 v149, v6, v8
	v_lshlrev_b32_e32 v6, 8, v12
	v_bitop3_b32 v7, v5, v12, 11 bitop3:0x78
	v_lshl_add_u32 v6, v7, 4, v6
	v_or_b32_e32 v150, v6, v8
	v_lshlrev_b32_e32 v6, 8, v14
	v_bitop3_b32 v7, v5, v14, 12 bitop3:0x78
	v_lshl_add_u32 v6, v7, 4, v6
	v_or_b32_e32 v151, v6, v8
	v_lshlrev_b32_e32 v6, 8, v15
	v_bitop3_b32 v7, v5, v15, 13 bitop3:0x78
	v_lshl_add_u32 v6, v7, 4, v6
	v_or_b32_e32 v152, v6, v8
	v_lshlrev_b32_e32 v6, 8, v17
	v_bitop3_b32 v7, v5, v17, 14 bitop3:0x78
	v_lshl_add_u32 v6, v7, 4, v6
	v_or_b32_e32 v153, v6, v8
	v_lshlrev_b32_e32 v6, 8, v19
	v_bitop3_b32 v5, v5, v19, 15 bitop3:0x78
	v_lshl_add_u32 v5, v5, 4, v6
	v_lshlrev_b32_e32 v114, 2, v3
	v_and_b32_e32 v13, 15, v115
	v_or_b32_e32 v154, v5, v8
	v_bitop3_b32 v5, v3, v115, 15 bitop3:0x78
	v_lshlrev_b32_e32 v155, 4, v5
	v_bitop3_b32 v5, v3, v13, 2 bitop3:0x36
	v_or_b32_e32 v8, 3, v114
	v_or_b32_e32 v11, 2, v114
	v_lshlrev_b32_e32 v156, 4, v5
	v_bitop3_b32 v5, v3, v13, 4 bitop3:0x36
	v_cmp_gt_u32_e64 s[48:49], v8, v4
	v_cmp_gt_u32_e64 s[50:51], v11, v4
	v_or_b32_e32 v8, 9, v114
	v_or_b32_e32 v11, 8, v114
	v_lshlrev_b32_e32 v157, 4, v5
	v_bitop3_b32 v5, v3, v13, 6 bitop3:0x36
	v_cmp_gt_u32_e64 s[52:53], v8, v4
	v_cmp_gt_u32_e64 s[54:55], v11, v4
	v_or_b32_e32 v8, 11, v114
	v_or_b32_e32 v11, 10, v114
	v_lshlrev_b32_e32 v158, 4, v5
	v_bitop3_b32 v5, v3, v13, 8 bitop3:0x36
	v_cmp_gt_u32_e64 s[56:57], v8, v4
	v_cmp_gt_u32_e64 s[58:59], v11, v4
	v_or_b32_e32 v8, 17, v114
	v_or_b32_e32 v11, 16, v114
	v_lshlrev_b32_e32 v159, 4, v5
	v_bitop3_b32 v5, v3, v13, 10 bitop3:0x36
	v_cmp_gt_u32_e64 s[60:61], v8, v4
	v_cmp_gt_u32_e64 s[62:63], v11, v4
	v_or_b32_e32 v8, 19, v114
	v_or_b32_e32 v11, 18, v114
	v_lshlrev_b32_e32 v2, 3, v115
	v_bfe_u32 v10, v115, 2, 2
	v_lshlrev_b32_e32 v160, 4, v5
	v_bitop3_b32 v5, v3, v13, 12 bitop3:0x36
	v_cmp_gt_u32_e64 s[64:65], v8, v4
	v_cmp_gt_u32_e64 s[66:67], v11, v4
	v_or_b32_e32 v8, 25, v114
	v_or_b32_e32 v11, 24, v114
	v_and_b32_e32 v0, 0x78, v2
	v_lshlrev_b32_e32 v135, 6, v1
	v_lshlrev_b32_e32 v1, 4, v115
	v_lshrrev_b32_e32 v9, 2, v115
	v_lshrrev_b32_e32 v16, 2, v15
	v_lshrrev_b32_e32 v18, 2, v17
	v_lshrrev_b32_e32 v20, 2, v19
	v_lshlrev_b32_e32 v161, 4, v5
	v_bitop3_b32 v5, v3, v13, 14 bitop3:0x36
	v_lshlrev_b32_e32 v163, 4, v10
	v_cmp_gt_u32_e64 s[68:69], v8, v4
	v_cmp_gt_u32_e64 s[70:71], v11, v4
	v_or_b32_e32 v8, 27, v114
	v_or_b32_e32 v11, 26, v114
	v_lshlrev_b32_e32 v176, 1, v0
	v_and_b32_e32 v2, 56, v2
	v_or_b32_e32 v134, 0xffffffe0, v115
	v_bitop3_b32 v136, v1, 48, v115 bitop3:0x48
	v_add_u32_e32 v1, 0x10400, v135
	v_lshlrev_b32_e32 v141, 4, v3
	v_or_b32_e32 v143, 0x10e0, v4
	v_lshlrev_b32_e32 v162, 4, v5
	v_xor_b32_e32 v5, 16, v163
	v_xor_b32_e32 v6, 32, v163
	v_xor_b32_e32 v7, 48, v163
	v_cmp_gt_u32_e64 s[44:45], v114, v4
	v_cmp_lt_u32_e64 s[46:47], v114, v4
	v_cmp_gt_u32_e64 s[72:73], v8, v4
	v_cmp_gt_u32_e64 s[74:75], v11, v4
	v_bitop3_b32 v4, v3, v9, 3 bitop3:0x78
	v_bitop3_b32 v3, v3, v10, 2 bitop3:0x36
	v_mad_u32_u24 v166, v16, s2, v128
	v_mad_u32_u24 v167, v18, s2, v128
	v_mad_u32_u24 v168, v20, s2, v128
	s_add_i32 s88, s26, s3
	v_readlane_b32 s2, v252, 52
	v_lshl_add_u64 v[112:113], s[86:87], 0, v[176:177]
	v_cmp_gt_i32_e64 s[42:43], s27, v115
	s_ashr_i32 s9, s8, 31
	s_lshl_b32 s10, s10, 12
	v_lshlrev_b32_e32 v164, 4, v4
	v_lshlrev_b32_e32 v165, 4, v3
	v_sub_u32_e32 v169, 0, v134
	v_add_u32_e32 v170, 32, v132
	v_sub_u32_e32 v171, 0xffffffe0, v132
	v_add_u32_e32 v172, 32, v130
	v_sub_u32_e32 v173, 0xffffffe0, v130
	v_lshlrev_b32_e32 v176, 1, v0
	v_lshlrev_b32_e32 v116, 1, v2
	s_add_i32 s11, s26, 0x2080
	s_addk_i32 s88, 0x4100
	v_add_u32_e32 v174, v1, v136
	v_add_u32_e32 v175, v139, v5
	v_add_u32_e32 v178, v139, v6
	v_add_u32_e32 v179, v139, v7
	s_mov_b32 s89, s2
	v_readlane_b32 s3, v252, 53
	s_branch .LBB0_395

.LBB0_397:
	s_lshl_b32 s18, s3, 6
	s_and_b64 s[16:17], s[76:77], exec
	s_mov_b32 s3, 0x17500000
	s_cselect_b32 s16, s3, 0x1b900000
	s_add_u32 s16, s28, s16
	s_addc_u32 s17, s29, 0
	s_lshl_b32 s80, s18, 1
	s_add_u32 s20, s16, s80
	s_addc_u32 s21, s17, 0
	s_add_u32 s34, s20, s2
	s_addc_u32 s35, s21, 0
	s_lshl_b64 s[20:21], s[8:9], 1
	s_waitcnt vmcnt(0)
	s_add_u32 s20, s34, s20
	v_mov_b32_e32 v14, v177
	v_mov_b32_e32 v15, v177
	s_addc_u32 s21, s35, s21
	v_lshlrev_b32_e32 v124, 1, v114
	v_mov_b32_e32 v125, v177
	v_mov_b32_e32 v0, v177
	v_mov_b32_e32 v1, v177
	v_mov_b32_e32 v2, v177
	v_mov_b32_e32 v3, v177
	v_mov_b32_e32 v4, v177
	v_mov_b32_e32 v5, v177
	v_mov_b32_e32 v6, v177
	v_mov_b32_e32 v7, v177
	v_mov_b32_e32 v8, v177
	v_mov_b32_e32 v9, v177
	v_mov_b32_e32 v10, v177
	v_mov_b32_e32 v11, v177
	v_mov_b32_e32 v12, v177
	v_mov_b32_e32 v13, v177
	v_mov_b64_e32 v[30:31], v[14:15]
	v_mov_b64_e32 v[46:47], v[14:15]
	v_mov_b64_e32 v[62:63], v[14:15]
	v_mov_b64_e32 v[78:79], v[14:15]
	s_mov_b32 s3, 0
	s_mov_b32 s24, 1
	v_lshl_add_u64 v[126:127], s[20:21], 0, v[124:125]
	v_mov_b32_e32 v117, v173
	v_mov_b32_e32 v125, v171
	v_mov_b32_e32 v180, v169
	v_mov_b64_e32 v[28:29], v[12:13]
	v_mov_b64_e32 v[26:27], v[10:11]
	v_mov_b64_e32 v[24:25], v[8:9]
	v_mov_b64_e32 v[22:23], v[6:7]
	v_mov_b64_e32 v[20:21], v[4:5]
	v_mov_b64_e32 v[18:19], v[2:3]
	v_mov_b64_e32 v[16:17], v[0:1]
	v_mov_b64_e32 v[44:45], v[12:13]
	v_mov_b64_e32 v[42:43], v[10:11]
	v_mov_b64_e32 v[40:41], v[8:9]
	v_mov_b64_e32 v[38:39], v[6:7]
	v_mov_b64_e32 v[36:37], v[4:5]
	v_mov_b64_e32 v[34:35], v[2:3]
	v_mov_b64_e32 v[32:33], v[0:1]
	v_mov_b64_e32 v[60:61], v[12:13]
	v_mov_b64_e32 v[58:59], v[10:11]
	v_mov_b64_e32 v[56:57], v[8:9]
	v_mov_b64_e32 v[54:55], v[6:7]
	v_mov_b64_e32 v[52:53], v[4:5]
	v_mov_b64_e32 v[50:51], v[2:3]
	v_mov_b64_e32 v[48:49], v[0:1]
	v_mov_b64_e32 v[76:77], v[12:13]
	v_mov_b64_e32 v[74:75], v[10:11]
	v_mov_b64_e32 v[72:73], v[8:9]
	v_mov_b64_e32 v[70:71], v[6:7]
	v_mov_b64_e32 v[68:69], v[4:5]
	v_mov_b64_e32 v[66:67], v[2:3]
	v_mov_b64_e32 v[64:65], v[0:1]
	s_waitcnt vmcnt(0) lgkmcnt(0)
	s_barrier
	s_mov_b32 s98, 0
	s_mov_b32 s99, 0xb400
	v_add_u32_e32 v141, 0xb400, v141
	v_add_u32_e32 v175, 0xb400, v175
	v_add_u32_e32 v178, 0xb400, v178
	v_add_u32_e32 v179, 0xb400, v179
	s_branch .LBB0_399
.LBB0_398:
	s_waitcnt vmcnt(0)
	s_add_i32 s3, s3, 32
	s_add_i32 s24, s24, 1
	v_subrev_u32_e32 v147, s98, v147
	v_add_u32_e32 v147, s99, v147
	v_subrev_u32_e32 v148, s98, v148
	v_add_u32_e32 v148, s99, v148
	v_subrev_u32_e32 v149, s98, v149
	v_add_u32_e32 v149, s99, v149
	v_subrev_u32_e32 v150, s98, v150
	v_add_u32_e32 v150, s99, v150
	v_subrev_u32_e32 v151, s98, v151
	v_add_u32_e32 v151, s99, v151
	v_subrev_u32_e32 v152, s98, v152
	v_add_u32_e32 v152, s99, v152
	v_subrev_u32_e32 v153, s98, v153
	v_add_u32_e32 v153, s99, v153
	v_subrev_u32_e32 v154, s98, v154
	v_add_u32_e32 v154, s99, v154
	v_subrev_u32_e32 v141, s99, v141
	v_add_u32_e32 v141, s98, v141
	v_subrev_u32_e32 v175, s99, v175
	v_add_u32_e32 v175, s98, v175
	v_subrev_u32_e32 v178, s99, v178
	v_add_u32_e32 v178, s98, v178
	v_subrev_u32_e32 v179, s99, v179
	v_add_u32_e32 v179, s98, v179
	s_sub_u32 s98, 0xb400, s98
	s_sub_u32 s99, 0xb400, s99
	v_subrev_u32_e32 v180, 32, v180
	v_subrev_u32_e32 v125, 32, v125
	s_cmpk_eq_i32 s3, 0x1120
	v_subrev_u32_e32 v117, 32, v117
	s_waitcnt lgkmcnt(0)
	s_barrier
	s_cbranch_scc1 .LBB0_414
.LBB0_399:
	s_cmpk_ge_i32 s3, 0x10e0
	s_cbranch_scc1 .LBB0_402
	v_add_u32_e32 v80, s3, v172
	v_cmp_lt_i32_e32 vcc, s33, v80
	s_bitcmp1_b32 s24, 0
	s_cselect_b32 s20, 0x5200, 0
	v_cndmask_b32_e32 v81, v207, v208, vcc
	v_add_u32_e32 v81, v81, v117
	v_cndmask_b32_e64 v80, v81, v80, s[76:77]
	v_ashrrev_i32_e32 v81, 31, v80
	v_lshl_add_u64 v[80:81], s[82:83], 0, v[80:81]
	v_lshlrev_b64 v[80:81], 12, v[80:81]
	s_add_i32 s21, s20, s26
	v_lshl_add_u64 v[82:83], v[118:119], 0, v[80:81]
	s_mov_b32 m0, s21
	v_lshl_add_u64 v[80:81], v[120:121], 0, v[80:81]
	global_load_lds_dwordx4 v[82:83], off
	s_add_i32 m0, s21, 0x2080
	s_and_b64 vcc, exec, s[78:79]
	global_load_lds_dwordx4 v[80:81], off
	s_cbranch_vccnz .LBB0_402
	v_add_u32_e32 v80, s3, v170
	v_cmp_lt_i32_e32 vcc, s33, v80
	s_add_i32 s20, s20, s6
	s_add_i32 m0, s20, 0x4100
	v_cndmask_b32_e32 v81, v207, v208, vcc
	v_add_u32_e32 v81, v81, v125
	v_cndmask_b32_e64 v80, v81, v80, s[76:77]
	v_ashrrev_i32_e32 v81, 31, v80
	v_lshl_add_u64 v[80:81], s[82:83], 0, v[80:81]
	v_lshlrev_b64 v[80:81], 12, v[80:81]
	v_lshl_add_u64 v[80:81], v[122:123], 0, v[80:81]
	global_load_lds_dwordx4 v[80:81], off
.LBB0_402:
	s_cmp_lt_u32 s3, 64
	s_cselect_b64 s[20:21], -1, 0
	s_cmp_eq_u32 s100, 0
	s_cselect_b64 vcc, -1, 0
	s_or_b64 s[20:21], vcc, s[20:21]
	s_and_b64 vcc, exec, s[20:21]
	s_cbranch_vccnz .Lscan_D
	v_add_u32_e32 v80, s3, v134
	v_subrev_u32_e32 v80, 32, v80
	v_cmp_lt_i32_e32 vcc, s33, v80
	v_add_u32_e32 v86, s7, v129
	v_add_u32_e32 v86, s98, v86
	ds_read2st64_b32 v[64:65], v86 offset0:32 offset1:33
	ds_read2st64_b32 v[66:67], v86 offset0:34 offset1:35
	ds_read2st64_b32 v[68:69], v86 offset0:36 offset1:37
	ds_read2st64_b32 v[70:71], v86 offset0:38 offset1:39
	ds_read2st64_b32 v[72:73], v86 offset0:40 offset1:41
	ds_read2st64_b32 v[74:75], v86 offset0:42 offset1:43
	ds_read2st64_b32 v[76:77], v86 offset0:44 offset1:45
	ds_read2st64_b32 v[78:79], v86 offset0:46 offset1:47
	ds_read2st64_b32 v[82:83], v86 offset1:1
	ds_read2st64_b32 v[84:85], v86 offset0:2 offset1:3
	v_cndmask_b32_e32 v81, v207, v208, vcc
	v_add_u32_e32 v81, v81, v180
	v_add_u32_e32 v81, 32, v81
	v_cndmask_b32_e64 v80, v81, v80, s[76:77]
	v_ashrrev_i32_e32 v81, 31, v80
	v_lshl_add_u64 v[80:81], s[82:83], 0, v[80:81]
	v_lshlrev_b64 v[80:81], 12, v[80:81]
	s_waitcnt lgkmcnt(0)
	v_pk_add_f32 v[82:83], v[64:65], v[82:83]
	v_pk_add_f32 v[84:85], v[66:67], v[84:85]
	v_lshl_add_u64 v[80:81], v[126:127], 0, v[80:81]
	v_cvt_pk_bf16_f32 v82, v82, v83
	v_cvt_pk_bf16_f32 v83, v84, v85
	global_store_dwordx2 v[80:81], v[82:83], off
	ds_read2st64_b32 v[82:83], v86 offset0:4 offset1:5
	ds_read2st64_b32 v[84:85], v86 offset0:6 offset1:7
	s_waitcnt lgkmcnt(0)
	v_pk_add_f32 v[82:83], v[68:69], v[82:83]
	v_pk_add_f32 v[84:85], v[70:71], v[84:85]
	v_cvt_pk_bf16_f32 v82, v82, v83
	v_cvt_pk_bf16_f32 v83, v84, v85
	global_store_dwordx2 v[80:81], v[82:83], off offset:16
	ds_read2st64_b32 v[82:83], v86 offset0:8 offset1:9
	ds_read2st64_b32 v[84:85], v86 offset0:10 offset1:11
	s_waitcnt lgkmcnt(0)
	v_pk_add_f32 v[82:83], v[72:73], v[82:83]
	v_pk_add_f32 v[84:85], v[74:75], v[84:85]
	v_cvt_pk_bf16_f32 v82, v82, v83
	v_cvt_pk_bf16_f32 v83, v84, v85
	global_store_dwordx2 v[80:81], v[82:83], off offset:32
	ds_read2st64_b32 v[82:83], v86 offset0:12 offset1:13
	ds_read2st64_b32 v[84:85], v86 offset0:14 offset1:15
	s_waitcnt lgkmcnt(0)
	v_pk_add_f32 v[82:83], v[76:77], v[82:83]
	v_pk_add_f32 v[84:85], v[78:79], v[84:85]
	v_cvt_pk_bf16_f32 v82, v82, v83
	v_cvt_pk_bf16_f32 v83, v84, v85
	global_store_dwordx2 v[80:81], v[82:83], off offset:48
.Lscan_D:
	s_cmp_eq_u32 s3, 0
	s_cbranch_scc1 .Lscan_A
	s_mov_b64 s[20:21], -1
	s_and_b64 vcc, exec, s[12:13]
	s_cbranch_vccz .LBB0_412
	s_and_b64 vcc, exec, s[78:79]
	s_cbranch_vccnz .LBB0_411
	v_add3_u32 v84, v138, v155, s99
	ds_read_b128 v[80:83], v84 offset:50176
	ds_read_b128 v[84:87], v84 offset:41984
	v_add3_u32 v100, v138, v156, s99
	ds_read_b128 v[96:99], v100 offset:50176
	ds_read_b128 v[100:103], v100 offset:41984
	v_add3_u32 v181, v138, v157, s99
	ds_read_b128 v[182:185], v181 offset:50176
	ds_read_b128 v[186:189], v181 offset:41984
	s_waitcnt lgkmcnt(4)
	v_mfma_f32_32x32x16_bf16 v[80:95], v[80:83], v[84:87], 0
	v_add3_u32 v181, v138, v158, s99
	s_waitcnt lgkmcnt(2)
	v_mfma_f32_32x32x16_bf16 v[96:111], v[96:99], v[100:103], 0
	s_waitcnt lgkmcnt(0)
	v_mfma_f32_32x32x16_bf16 v[80:95], v[182:185], v[186:189], v[80:95]
	ds_read_b128 v[182:185], v181 offset:50176
	ds_read_b128 v[186:189], v181 offset:41984
	v_add3_u32 v181, v138, v159, s99
	s_waitcnt lgkmcnt(0)
	v_mfma_f32_32x32x16_bf16 v[96:111], v[182:185], v[186:189], v[96:111]
	ds_read_b128 v[182:185], v181 offset:50176
	ds_read_b128 v[186:189], v181 offset:41984
	v_add3_u32 v181, v138, v160, s99
	s_waitcnt lgkmcnt(0)
	v_mfma_f32_32x32x16_bf16 v[80:95], v[182:185], v[186:189], v[80:95]
	ds_read_b128 v[182:185], v181 offset:50176
	ds_read_b128 v[186:189], v181 offset:41984
	v_add3_u32 v181, v138, v161, s99
	s_waitcnt lgkmcnt(0)
	v_mfma_f32_32x32x16_bf16 v[96:111], v[182:185], v[186:189], v[96:111]
	ds_read_b128 v[182:185], v181 offset:50176
	ds_read_b128 v[186:189], v181 offset:41984
	v_add3_u32 v181, v138, v162, s99
	s_waitcnt lgkmcnt(0)
	v_mfma_f32_32x32x16_bf16 v[80:95], v[182:185], v[186:189], v[80:95]
	ds_read_b128 v[182:185], v181 offset:50176
	ds_read_b128 v[186:189], v181 offset:41984
	v_add3_u32 v181, v139, v163, s99
	ds_read_b64 v[190:191], v181
	ds_read_b64 v[192:193], v175
	ds_read_b64 v[194:195], v178
	ds_read_b64 v[196:197], v179
	s_waitcnt lgkmcnt(4)
	v_mfma_f32_32x32x16_bf16 v[96:111], v[182:185], v[186:189], v[96:111]
	s_nop 11
	v_add_f32_e32 v80, v80, v96
	v_add_f32_e32 v81, v81, v97
	v_cndmask_b32_e64 v80, v80, 0, s[44:45]
	v_cndmask_b32_e64 v81, 0, v81, s[46:47]
	v_pk_add_f32 v[82:83], v[82:83], v[98:99]
	v_cvt_pk_bf16_f32 v80, v80, v81
	v_cvt_pk_bf16_f32 v81, v82, v83
	v_cndmask_b32_e64 v82, v81, 0, s[50:51]
	v_lshrrev_b32_e32 v81, 16, v81
	v_pk_add_f32 v[84:85], v[84:85], v[100:101]
	v_cndmask_b32_e64 v81, v81, 0, s[48:49]
	v_perm_b32 v81, v81, v82, s85
	v_cvt_pk_bf16_f32 v82, v84, v85
	v_cndmask_b32_e64 v83, v82, 0, s[54:55]
	v_lshrrev_b32_e32 v82, 16, v82
	v_pk_add_f32 v[86:87], v[86:87], v[102:103]
	v_cndmask_b32_e64 v82, v82, 0, s[52:53]
	v_perm_b32 v82, v82, v83, s85
	v_cvt_pk_bf16_f32 v83, v86, v87
	v_cndmask_b32_e64 v84, v83, 0, s[58:59]
	v_lshrrev_b32_e32 v83, 16, v83
	v_pk_add_f32 v[88:89], v[88:89], v[104:105]
	v_cndmask_b32_e64 v83, v83, 0, s[56:57]
	v_perm_b32 v83, v83, v84, s85
	v_cvt_pk_bf16_f32 v84, v88, v89
	v_cndmask_b32_e64 v85, v84, 0, s[62:63]
	v_lshrrev_b32_e32 v84, 16, v84
	v_pk_add_f32 v[90:91], v[90:91], v[106:107]
	v_cndmask_b32_e64 v84, v84, 0, s[60:61]
	v_perm_b32 v96, v84, v85, s85
	v_cvt_pk_bf16_f32 v84, v90, v91
	v_cndmask_b32_e64 v85, v84, 0, s[66:67]
	v_lshrrev_b32_e32 v84, 16, v84
	v_pk_add_f32 v[92:93], v[92:93], v[108:109]
	v_cndmask_b32_e64 v84, v84, 0, s[64:65]
	v_perm_b32 v97, v84, v85, s85
	v_cvt_pk_bf16_f32 v84, v92, v93
	v_pk_add_f32 v[110:111], v[94:95], v[110:111]
	v_cndmask_b32_e64 v98, v84, 0, s[70:71]
	v_lshrrev_b32_e32 v99, 16, v84
	s_waitcnt lgkmcnt(2)
	v_mfma_f32_32x32x16_bf16 v[80:95], v[190:193], v[80:83], 0
	v_cndmask_b32_e64 v99, v99, 0, s[68:69]
	v_perm_b32 v98, v99, v98, s85
	v_cvt_pk_bf16_f32 v99, v110, v111
	v_cndmask_b32_e64 v100, v99, 0, s[74:75]
	v_lshrrev_b32_e32 v99, 16, v99
	v_cndmask_b32_e64 v99, v99, 0, s[72:73]
	v_perm_b32 v99, v99, v100, s85
	s_waitcnt lgkmcnt(0)
	s_nop 0
	v_mfma_f32_32x32x16_bf16 v[80:95], v[194:197], v[96:99], v[80:95]
	v_add_u32_e32 v96, s10, v129
	v_add_u32_e32 v96, s99, v96
	s_nop 10
	ds_write2st64_b32 v96, v80, v81 offset1:1
	ds_write2st64_b32 v96, v82, v83 offset0:2 offset1:3
	ds_write2st64_b32 v96, v84, v85 offset0:4 offset1:5
	ds_write2st64_b32 v96, v86, v87 offset0:6 offset1:7
	ds_write2st64_b32 v96, v88, v89 offset0:8 offset1:9
	ds_write2st64_b32 v96, v90, v91 offset0:10 offset1:11
	ds_write2st64_b32 v96, v92, v93 offset0:12 offset1:13
	ds_write2st64_b32 v96, v94, v95 offset0:14 offset1:15

.LBB0_412:
	s_andn2_b64 vcc, exec, s[20:21]
	s_cbranch_vccnz .Lscan_A
	v_add3_u32 v64, v138, v155, s99
	v_add3_u32 v68, v138, v156, s99
	ds_read_b128 v[64:67], v64 offset:41984
	ds_read_b128 v[80:83], v68 offset:41984
	v_add_u32_e32 v68, 0x11400, v141
	v_add_u32_e32 v72, 0x11420, v141
	v_add_u32_e32 v76, 0x11440, v141
	v_add_u32_e32 v84, 0x11460, v141
	ds_read_b128 v[68:71], v68
	ds_read_b128 v[72:75], v72
	ds_read_b128 v[76:79], v76
	ds_read_b128 v[84:87], v84
	v_add_u32_e32 v104, 0x11480, v141
	v_add_u32_e32 v108, 0x114a0, v141
	s_waitcnt lgkmcnt(3)
	v_pk_mul_f32 v[68:69], v[0:1], v[68:69]
	v_pk_mul_f32 v[70:71], v[2:3], v[70:71]
	v_cvt_pk_bf16_f32 v68, v68, v69
	v_cvt_pk_bf16_f32 v69, v70, v71
	s_waitcnt lgkmcnt(2)
	v_pk_mul_f32 v[70:71], v[4:5], v[72:73]
	v_pk_mul_f32 v[72:73], v[6:7], v[74:75]
	s_waitcnt lgkmcnt(0)
	v_pk_mul_f32 v[84:85], v[12:13], v[84:85]
	v_cvt_pk_bf16_f32 v70, v70, v71
	v_cvt_pk_bf16_f32 v71, v72, v73
	v_cvt_pk_bf16_f32 v90, v84, v85
	v_pk_mul_f32 v[84:85], v[14:15], v[86:87]
	v_pk_mul_f32 v[72:73], v[8:9], v[76:77]
	v_cvt_pk_bf16_f32 v91, v84, v85
	v_add3_u32 v84, v138, v157, s99
	v_add3_u32 v85, v138, v158, s99
	ds_read_b128 v[96:99], v84 offset:41984
	ds_read_b128 v[100:103], v85 offset:41984
	ds_read_b128 v[104:107], v104
	ds_read_b128 v[108:111], v108
	v_cvt_pk_bf16_f32 v88, v72, v73
	v_pk_mul_f32 v[72:73], v[10:11], v[78:79]
	v_add_u32_e32 v181, 0x114c0, v141
	v_cvt_pk_bf16_f32 v89, v72, v73
	v_mfma_f32_32x32x16_bf16 v[64:79], v[68:71], v[64:67], 0
	s_waitcnt lgkmcnt(1)
	v_mul_f32_e64 v104, v16, v104
	v_mul_f32_e64 v105, v17, v105
	v_mul_f32_e64 v106, v18, v106
	v_mul_f32_e64 v107, v19, v107
	v_add_u32_e32 v186, 0x114e0, v141
	v_cvt_pk_bf16_f32 v104, v104, v105
	v_cvt_pk_bf16_f32 v105, v106, v107
	s_waitcnt lgkmcnt(0)
	v_pk_mul_f32 v[106:107], v[20:21], v[108:109]
	v_pk_mul_f32 v[108:109], v[22:23], v[110:111]
	ds_read_b128 v[182:185], v181
	ds_read_b128 v[186:189], v186
	v_cvt_pk_bf16_f32 v106, v106, v107
	v_cvt_pk_bf16_f32 v107, v108, v109
	v_mfma_f32_32x32x16_bf16 v[80:95], v[88:91], v[80:83], 0
	s_waitcnt lgkmcnt(1)
	v_mul_f32_e64 v108, v24, v182
	v_mul_f32_e64 v109, v25, v183
	v_mul_f32_e64 v110, v26, v184
	v_mul_f32_e64 v111, v27, v185
	v_cvt_pk_bf16_f32 v108, v108, v109
	v_cvt_pk_bf16_f32 v109, v110, v111
	s_waitcnt lgkmcnt(0)
	v_pk_mul_f32 v[110:111], v[28:29], v[186:187]
	v_add_u32_e32 v181, 0x11540, v141
	v_cvt_pk_bf16_f32 v110, v110, v111
	v_mfma_f32_32x32x16_bf16 v[64:79], v[104:107], v[96:99], v[64:79]
	v_mul_f32_e64 v96, v30, v188
	v_mul_f32_e64 v97, v31, v189
	v_add3_u32 v104, v138, v160, s99
	v_cvt_pk_bf16_f32 v111, v96, v97
	v_add3_u32 v96, v138, v159, s99
	ds_read_b128 v[96:99], v96 offset:41984
	ds_read_b128 v[104:107], v104 offset:41984
	v_add_u32_e32 v186, 0x11560, v141
	v_add3_u32 v198, v140, v164, s99
	v_mfma_f32_32x32x16_bf16 v[80:95], v[108:111], v[100:103], v[80:95]
	v_add_u32_e32 v100, 0x11500, v141
	v_add_u32_e32 v108, 0x11520, v141
	ds_read_b128 v[100:103], v100
	ds_read_b128 v[108:111], v108
	ds_read_b128 v[182:185], v181
	ds_read_b128 v[186:189], v186
	v_add_u32_e32 v181, 0x115c0, v141
	v_add3_u32 v212, v140, v165, s99
	s_waitcnt lgkmcnt(3)
	v_pk_mul_f32 v[100:101], v[32:33], v[100:101]
	v_pk_mul_f32 v[102:103], v[34:35], v[102:103]
	v_cvt_pk_bf16_f32 v100, v100, v101
	v_cvt_pk_bf16_f32 v101, v102, v103
	s_waitcnt lgkmcnt(2)
	v_pk_mul_f32 v[102:103], v[36:37], v[108:109]
	v_pk_mul_f32 v[108:109], v[38:39], v[110:111]
	v_cvt_pk_bf16_f32 v102, v102, v103
	v_cvt_pk_bf16_f32 v103, v108, v109
	s_waitcnt lgkmcnt(1)
	v_pk_mul_f32 v[108:109], v[40:41], v[182:183]
	v_pk_mul_f32 v[110:111], v[42:43], v[184:185]
	v_cvt_pk_bf16_f32 v108, v108, v109
	v_cvt_pk_bf16_f32 v109, v110, v111
	s_waitcnt lgkmcnt(0)
	v_pk_mul_f32 v[110:111], v[44:45], v[186:187]
	v_mfma_f32_32x32x16_bf16 v[64:79], v[100:103], v[96:99], v[64:79]
	v_mul_f32_e64 v96, v46, v188
	v_mul_f32_e64 v97, v47, v189
	v_cvt_pk_bf16_f32 v110, v110, v111
	v_cvt_pk_bf16_f32 v111, v96, v97
	v_add3_u32 v96, v138, v161, s99
	v_add3_u32 v100, v138, v162, s99
	ds_read_b128 v[96:99], v96 offset:41984
	ds_read_b128 v[100:103], v100 offset:41984
	v_add_u32_e32 v186, 0x115e0, v141
	v_mfma_f32_32x32x16_bf16 v[80:95], v[108:111], v[104:107], v[80:95]
	v_add_u32_e32 v104, 0x11580, v141
	v_add_u32_e32 v108, 0x115a0, v141
	ds_read_b128 v[104:107], v104
	ds_read_b128 v[108:111], v108
	ds_read_b128 v[182:185], v181
	ds_read_b128 v[186:189], v186
	v_add3_u32 v181, v142, v164, s99
	v_add_u32_e32 v190, 0x11600, v141
	s_waitcnt lgkmcnt(3)
	v_pk_mul_f32 v[104:105], v[48:49], v[104:105]
	v_pk_mul_f32 v[106:107], v[50:51], v[106:107]
	v_cvt_pk_bf16_f32 v104, v104, v105
	v_cvt_pk_bf16_f32 v105, v106, v107
	s_waitcnt lgkmcnt(2)
	v_pk_mul_f32 v[106:107], v[52:53], v[108:109]
	v_pk_mul_f32 v[108:109], v[54:55], v[110:111]
	v_cvt_pk_bf16_f32 v106, v106, v107
	v_cvt_pk_bf16_f32 v107, v108, v109
	s_waitcnt lgkmcnt(1)
	v_pk_mul_f32 v[108:109], v[56:57], v[182:183]
	v_pk_mul_f32 v[110:111], v[58:59], v[184:185]
	v_cvt_pk_bf16_f32 v108, v108, v109
	v_cvt_pk_bf16_f32 v109, v110, v111
	s_waitcnt lgkmcnt(0)
	v_pk_mul_f32 v[110:111], v[60:61], v[186:187]
	v_mfma_f32_32x32x16_bf16 v[64:79], v[104:107], v[96:99], v[64:79]
	v_mul_f32_e64 v96, v62, v188
	v_mul_f32_e64 v97, v63, v189
	v_cvt_pk_bf16_f32 v110, v110, v111
	v_cvt_pk_bf16_f32 v111, v96, v97
	v_add_u32_e32 v194, 0x11620, v141
	v_add_u32_e32 v182, 0x11640, v141
	v_add_u32_e32 v186, 0x11660, v141
	v_add3_u32 v211, v142, v165, s99
	v_mfma_f32_32x32x16_bf16 v[80:95], v[108:111], v[100:103], v[80:95]
	ds_read_b128 v[96:99], v181 offset:58368
	ds_read_b128 v[100:103], v181 offset:60416
	ds_read_b128 v[104:107], v211 offset:58368
	ds_read_b128 v[108:111], v211 offset:60416
	ds_read_b128 v[182:185], v182
	ds_read_b128 v[186:189], v186
	ds_read_b128 v[190:193], v190
	ds_read_b128 v[194:197], v194
	ds_read_b128 v[198:201], v198
	ds_read_b128 v[212:215], v212
	s_waitcnt lgkmcnt(4)
	v_pk_mul_f32 v[12:13], v[12:13], v[186:187]
	v_pk_mul_f32 v[8:9], v[8:9], v[182:183]
	s_waitcnt lgkmcnt(2)
	v_pk_mul_f32 v[4:5], v[4:5], v[194:195]
	v_pk_mul_f32 v[14:15], v[14:15], v[188:189]
	v_pk_mul_f32 v[10:11], v[10:11], v[184:185]
	v_pk_mul_f32 v[6:7], v[6:7], v[196:197]
	v_pk_mul_f32 v[2:3], v[2:3], v[192:193]
	v_pk_mul_f32 v[0:1], v[0:1], v[190:191]
	v_add_u32_e32 v186, 0x11680, v141
	v_add_u32_e32 v190, 0x116a0, v141
	s_waitcnt lgkmcnt(1)
	v_mfma_f32_32x32x16_bf16 v[0:15], v[96:99], v[198:201], v[0:15]
	v_add_u32_e32 v96, 0x116c0, v141
	v_add_u32_e32 v182, 0x116e0, v141
	ds_read_b128 v[96:99], v96
	ds_read_b128 v[182:185], v182
	ds_read_b128 v[186:189], v186
	ds_read_b128 v[190:193], v190
	ds_read_b128 v[194:197], v211 offset:62464
	s_waitcnt lgkmcnt(4)
	v_pk_mul_f32 v[24:25], v[24:25], v[96:97]
	s_waitcnt lgkmcnt(3)
	v_pk_mul_f32 v[28:29], v[28:29], v[182:183]
	v_pk_mul_f32 v[30:31], v[30:31], v[184:185]
	s_waitcnt lgkmcnt(1)
	v_pk_mul_f32 v[20:21], v[20:21], v[190:191]
	v_pk_mul_f32 v[26:27], v[26:27], v[98:99]
	v_pk_mul_f32 v[22:23], v[22:23], v[192:193]
	v_pk_mul_f32 v[18:19], v[18:19], v[188:189]
	v_pk_mul_f32 v[16:17], v[16:17], v[186:187]
	v_mfma_f32_32x32x16_bf16 v[0:15], v[104:107], v[212:215], v[0:15]
	v_add_u32_e32 v104, 0x11700, v141
	v_add_u32_e32 v182, 0x11720, v141
	v_add_u32_e32 v96, 0x11740, v141
	v_add_f32_e64 v78, v78, v94
	v_add_f32_e64 v79, v79, v95
	v_pk_add_f32 v[76:77], v[76:77], v[92:93]
	v_pk_add_f32 v[74:75], v[74:75], v[90:91]
	v_pk_add_f32 v[72:73], v[72:73], v[88:89]
	v_mfma_f32_32x32x16_bf16 v[16:31], v[100:103], v[198:201], v[16:31]
	v_add_u32_e32 v100, 0x11760, v141
	ds_read_b128 v[96:99], v96
	ds_read_b128 v[100:103], v100
	ds_read_b128 v[104:107], v104
	ds_read_b128 v[182:185], v182
	ds_read_b128 v[186:189], v181 offset:62464
	ds_read_b128 v[190:193], v181 offset:64512
	s_waitcnt lgkmcnt(4)
	v_pk_mul_f32 v[44:45], v[44:45], v[100:101]
	v_pk_mul_f32 v[40:41], v[40:41], v[96:97]
	s_waitcnt lgkmcnt(3)
	v_pk_mul_f32 v[32:33], v[32:33], v[104:105]
	v_add_u32_e32 v104, 0x11780, v141
	v_add_u32_e32 v96, 0x117c0, v141
	v_mfma_f32_32x32x16_bf16 v[16:31], v[108:111], v[212:215], v[16:31]
	v_add_u32_e32 v108, 0x117a0, v141
	v_add_u32_e32 v100, 0x117e0, v141
	s_waitcnt lgkmcnt(2)
	v_mul_f32_e64 v36, v36, v182
	v_mul_f32_e64 v37, v37, v183
	v_pk_mul_f32 v[46:47], v[46:47], v[102:103]
	v_pk_mul_f32 v[42:43], v[42:43], v[98:99]
	v_pk_mul_f32 v[38:39], v[38:39], v[184:185]
	v_pk_mul_f32 v[34:35], v[34:35], v[106:107]
	ds_read_b128 v[96:99], v96
	ds_read_b128 v[100:103], v100
	ds_read_b128 v[104:107], v104
	ds_read_b128 v[108:111], v108
	ds_read_b128 v[182:185], v211 offset:64512
	s_waitcnt lgkmcnt(4)
	v_pk_mul_f32 v[56:57], v[56:57], v[96:97]
	s_waitcnt lgkmcnt(3)
	v_pk_mul_f32 v[60:61], v[60:61], v[100:101]
	v_pk_mul_f32 v[62:63], v[62:63], v[102:103]
	s_waitcnt lgkmcnt(1)
	v_pk_mul_f32 v[52:53], v[52:53], v[108:109]
	v_pk_mul_f32 v[58:59], v[58:59], v[98:99]
	v_pk_mul_f32 v[54:55], v[54:55], v[110:111]
	v_pk_mul_f32 v[50:51], v[50:51], v[106:107]
	v_pk_mul_f32 v[48:49], v[48:49], v[104:105]
	v_mfma_f32_32x32x16_bf16 v[32:47], v[186:189], v[198:201], v[32:47]
	v_add_f32_e64 v70, v70, v86
	v_add_f32_e64 v71, v71, v87
	v_add_f32_e64 v68, v68, v84
	v_add_f32_e64 v69, v69, v85
	v_add_f32_e64 v66, v66, v82
	v_add_f32_e64 v67, v67, v83
	v_pk_add_f32 v[64:65], v[64:65], v[80:81]
	v_mfma_f32_32x32x16_bf16 v[48:63], v[190:193], v[198:201], v[48:63]
	v_mfma_f32_32x32x16_bf16 v[32:47], v[194:197], v[212:215], v[32:47]
	s_waitcnt lgkmcnt(0)
	v_mfma_f32_32x32x16_bf16 v[48:63], v[182:185], v[212:215], v[48:63]
	v_add_u32_e32 v80, s7, v129
	v_add_u32_e32 v80, s99, v80
	ds_write2st64_b32 v80, v64, v65 offset0:32 offset1:33
	ds_write2st64_b32 v80, v66, v67 offset0:34 offset1:35
	ds_write2st64_b32 v80, v68, v69 offset0:36 offset1:37
	ds_write2st64_b32 v80, v70, v71 offset0:38 offset1:39
	ds_write2st64_b32 v80, v72, v73 offset0:40 offset1:41
	ds_write2st64_b32 v80, v74, v75 offset0:42 offset1:43
	ds_write2st64_b32 v80, v76, v77 offset0:44 offset1:45
	ds_write2st64_b32 v80, v78, v79 offset0:46 offset1:47
.Lscan_A:
	s_cmpk_eq_i32 s3, 0x1100
	s_cbranch_scc1 .LBB0_398
.LBB0_404:
	s_bitcmp1_b32 s24, 0
	s_cselect_b32 s20, 0, 0x5200
	v_add_u32_e32 v80, s20, v145
	ds_read_u16 v81, v80 offset:8320
	ds_read_u16 v82, v80
	ds_read_u16 v83, v80 offset:8576
	ds_read_u16 v84, v80 offset:8832
	ds_read_u16 v85, v80 offset:9088
	ds_read_u16 v86, v80 offset:768
	s_waitcnt lgkmcnt(0)
	v_lshlrev_b32_e32 v81, 16, v81
	ds_read_u16 v87, v80 offset:512
	ds_read_u16 v91, v80 offset:256
	v_add_f32_e32 v90, 0, v81
	v_mul_f32_e32 v80, 0x3fb8aa3b, v81
	v_lshlrev_b32_e32 v83, 16, v83
	v_lshlrev_b32_e32 v93, 16, v82
	v_exp_f32_e32 v82, v80
	v_add_f32_e32 v94, v90, v83
	v_lshlrev_b32_e32 v80, 16, v84
	v_add_f32_e32 v96, v94, v80
	v_mul_f32_e32 v80, 0x3fb8aa3b, v80
	v_exp_f32_e32 v84, v80
	v_lshlrev_b32_e32 v80, 16, v85
	s_waitcnt lgkmcnt(0)
	v_lshlrev_b32_e32 v95, 16, v87
	v_add_u32_e32 v81, s20, v146
	v_add_u32_e32 v85, s20, v166
	v_add_u32_e32 v87, s20, v168
	v_add_f32_e32 v101, v96, v80
	v_mul_f32_e32 v80, 0x3fb8aa3b, v80
	v_lshlrev_b32_e32 v97, 16, v86
	v_add_u32_e32 v86, s20, v167
	ds_read_u16 v88, v81 offset:8320
	ds_read_u16 v89, v85 offset:8576
	ds_read_u16 v92, v86 offset:8832
	ds_read_u16 v98, v87 offset:9088
	ds_read_u16 v99, v87 offset:768
	ds_read_u16 v100, v86 offset:512
	ds_read_u16 v87, v85 offset:256
	ds_read_u16 v81, v81
	v_exp_f32_e32 v85, v80
	s_waitcnt lgkmcnt(0)
	v_lshlrev_b32_e32 v80, 16, v88
	v_add_f32_e32 v103, v101, v80
	v_mul_f32_e32 v80, 0x3fb8aa3b, v80
	v_exp_f32_e32 v86, v80
	v_lshlrev_b32_e32 v80, 16, v89
	v_add_f32_e32 v105, v103, v80
	v_mul_f32_e32 v80, 0x3fb8aa3b, v80
	v_lshlrev_b32_e32 v104, 16, v87
	v_exp_f32_e32 v87, v80
	v_lshlrev_b32_e32 v80, 16, v92
	v_add_f32_e32 v106, v105, v80
	v_mul_f32_e32 v80, 0x3fb8aa3b, v80
	v_exp_f32_e32 v88, v80
	v_lshlrev_b32_e32 v80, 16, v98
	v_lshlrev_b32_e32 v102, 16, v81
	v_add_f32_e32 v81, v106, v80
	v_mul_f32_e32 v80, 0x3fb8aa3b, v80
	v_exp_f32_e32 v89, v80
	v_lshlrev_b32_e32 v98, 16, v99
	v_add_f32_dpp v80, v81, v81 quad_perm:[0,0,1,2] row_mask:0xf bank_mask:0xf bound_ctrl:1
	v_cndmask_b32_e64 v80, v80, v81, s[0:1]
	v_mul_f32_e32 v83, 0x3fb8aa3b, v83
	v_exp_f32_e32 v83, v83
	v_add_f32_dpp v92, v80, v80 quad_perm:[0,1,0,1] row_mask:0xf bank_mask:0xf bound_ctrl:1
	v_cndmask_b32_e64 v80, v80, v92, s[38:39]
	v_sub_f32_e32 v99, v80, v81
	v_add_f32_e32 v107, v81, v99
	v_add_f32_e32 v90, v90, v99
	v_mov_b32_dpp v80, v80 quad_perm:[3,3,3,3] row_mask:0xf bank_mask:0xf bound_ctrl:1
	v_mov_b32_dpp v81, v107 quad_perm:[1,1,1,1] row_mask:0xf bank_mask:0xf bound_ctrl:1
	v_sub_f32_e32 v90, v90, v81
	v_mul_f32_e32 v90, 0x3fb8aa3b, v90
	v_exp_f32_e32 v108, v90
	v_sub_f32_e32 v90, v80, v81
	v_mul_f32_e32 v90, 0x3fb8aa3b, v90
	v_exp_f32_e32 v90, v90
	v_mul_f32_e32 v93, v108, v93
	v_cvt_pk_bf16_f32 v93, v93, s0
	ds_write_b16 v147, v93 offset:41984
	v_add_f32_e32 v93, v94, v99
	v_sub_f32_e32 v93, v93, v81
	v_mul_f32_e32 v93, 0x3fb8aa3b, v93
	v_exp_f32_e32 v94, v93
	v_rcp_f32_e32 v92, v108
	v_lshlrev_b32_e32 v91, 16, v91
	v_pk_add_f32 v[82:83], v[82:83], 1.0 op_sel_hi:[1,0] neg_lo:[1,0] neg_hi:[1,0]
	v_rcp_f32_e32 v93, v94
	v_mul_f32_e32 v91, v94, v91
	v_cvt_pk_bf16_f32 v91, v91, s0
	v_pk_add_f32 v[84:85], v[84:85], 1.0 op_sel_hi:[1,0] neg_lo:[1,0] neg_hi:[1,0]
	v_pk_mul_f32 v[82:83], v[82:83], v[92:93]
	v_pk_add_f32 v[86:87], v[86:87], 1.0 op_sel_hi:[1,0] neg_lo:[1,0] neg_hi:[1,0]
	v_cvt_pk_bf16_f32 v92, v82, s0
	ds_write_b16 v147, v92 offset:50176
	ds_write_b16 v148, v91 offset:41984
	v_cvt_pk_bf16_f32 v91, v83, s0
	v_pk_mul_f32 v[82:83], v[90:91], v[82:83] op_sel_hi:[0,1]
	v_add_f32_e32 v92, v96, v99
	v_cvt_pk_bf16_f32 v82, v82, v83
	v_add_f32_e32 v83, v101, v99
	v_sub_f32_e32 v92, v92, v81
	v_sub_f32_e32 v83, v83, v81
	v_mul_f32_e32 v92, 0x3fb8aa3b, v92
	v_mul_f32_e32 v83, 0x3fb8aa3b, v83
	v_exp_f32_e32 v93, v92
	v_exp_f32_e32 v83, v83
	ds_write_b16 v148, v91 offset:50176
	v_lshlrev_b32_e32 v100, 16, v100
	v_rcp_f32_e32 v92, v93
	v_mul_f32_e32 v91, v93, v95
	v_rcp_f32_e32 v93, v83
	v_cvt_pk_bf16_f32 v91, v91, s0
	ds_write_b16 v149, v91 offset:41984
	v_mul_f32_e32 v83, v83, v97
	v_pk_mul_f32 v[84:85], v[84:85], v[92:93]
	v_cvt_pk_bf16_f32 v83, v83, s0
	v_cvt_pk_bf16_f32 v91, v84, s0
	ds_write_b16 v149, v91 offset:50176
	ds_write_b16 v150, v83 offset:41984
	v_add_f32_e32 v91, v103, v99
	v_sub_f32_e32 v91, v91, v81
	v_mul_f32_e32 v91, 0x3fb8aa3b, v91
	v_exp_f32_e32 v91, v91
	v_cvt_pk_bf16_f32 v83, v85, s0
	ds_write_b16 v150, v83 offset:50176
	v_pk_add_f32 v[88:89], v[88:89], 1.0 op_sel_hi:[1,0] neg_lo:[1,0] neg_hi:[1,0]
	v_pk_mul_f32 v[84:85], v[90:91], v[84:85] op_sel_hi:[0,1]
	v_cvt_pk_bf16_f32 v83, v84, v85
	v_add_f32_e32 v85, v105, v99
	v_sub_f32_e32 v85, v85, v81
	v_mul_f32_e32 v85, 0x3fb8aa3b, v85
	v_exp_f32_e32 v92, v85
	v_mul_f32_e32 v85, v91, v102
	v_cvt_pk_bf16_f32 v85, v85, s0
	v_rcp_f32_e32 v84, v91
	ds_write_b16 v151, v85 offset:41984
	v_rcp_f32_e32 v85, v92
	v_mul_f32_e32 v91, v92, v104
	v_cvt_pk_bf16_f32 v91, v91, s0
	v_pk_mul_f32 v[84:85], v[86:87], v[84:85]
	v_add_f32_e32 v87, v106, v99
	v_cvt_pk_bf16_f32 v86, v84, s0
	v_sub_f32_e32 v87, v87, v81
	ds_write_b16 v151, v86 offset:50176
	ds_write_b16 v152, v91 offset:41984
	v_cvt_pk_bf16_f32 v86, v85, s0
	v_mul_f32_e32 v87, 0x3fb8aa3b, v87
	v_pk_mul_f32 v[84:85], v[90:91], v[84:85] op_sel_hi:[0,1]
	v_exp_f32_e32 v87, v87
	v_cvt_pk_bf16_f32 v84, v84, v85
	v_sub_f32_e32 v85, v107, v81
	v_mul_f32_e32 v85, 0x3fb8aa3b, v85
	v_exp_f32_e32 v85, v85
	ds_write_b16 v152, v86 offset:50176
	v_rcp_f32_e32 v86, v87
	v_mul_f32_e32 v87, v87, v100
	v_cvt_pk_bf16_f32 v87, v87, s0
	ds_write_b16 v153, v87 offset:41984
	v_rcp_f32_e32 v87, v85
	v_mul_f32_e32 v85, v85, v98
	v_cvt_pk_bf16_f32 v85, v85, s0
	v_pk_mul_f32 v[86:87], v[88:89], v[86:87]
	s_nop 0
	v_cvt_pk_bf16_f32 v88, v86, s0
	ds_write_b16 v153, v88 offset:50176
	ds_write_b16 v154, v85 offset:41984
	v_cvt_pk_bf16_f32 v85, v87, s0
	v_pk_mul_f32 v[86:87], v[90:91], v[86:87] op_sel_hi:[0,1]
	ds_write_b16 v154, v85 offset:50176
	v_cvt_pk_bf16_f32 v85, v86, v87
	v_add3_u32 v86, v135, v136, s98
	ds_write_b128 v86, v[82:85] offset:58368
	s_and_saveexec_b64 vcc, s[0:1]
	s_cbranch_execz .LBB0_406
	v_mul_f32_e32 v81, 0x3fb8aa3b, v81
	v_exp_f32_e32 v81, v81
	v_mul_f32_e32 v80, 0x3fb8aa3b, v80
	v_exp_f32_e32 v80, v80
	v_add_u32_e32 v82, 0x11400, v115
	v_add_u32_e32 v82, s98, v82
	ds_write_b32 v82, v81
	v_add_u32_e32 v81, 0x11600, v115
	v_add_u32_e32 v81, s98, v81
	ds_write_b32 v81, v80
.LBB0_406:
	s_or_b64 exec, exec, vcc
	s_and_saveexec_b64 vcc, s[42:43]
	s_cbranch_execz .LBB0_408
	v_add3_u32 v83, s20, v137, v128
	ds_read_u16 v80, v83 offset:16640
	ds_read_u16 v81, v83 offset:16768
	s_waitcnt lgkmcnt(0)
	v_lshl_or_b32 v80, v81, 16, v80
	ds_read_u16 v81, v83 offset:16896
	ds_read_u16 v82, v83 offset:17024
	s_waitcnt lgkmcnt(0)
	v_lshl_or_b32 v81, v82, 16, v81
	ds_read_u16 v82, v83 offset:17152
	ds_read_u16 v84, v83 offset:17280
	s_waitcnt lgkmcnt(0)
	v_lshl_or_b32 v82, v84, 16, v82
	ds_read_u16 v84, v83 offset:17408
	ds_read_u16 v83, v83 offset:17536
	s_waitcnt lgkmcnt(0)
	v_lshl_or_b32 v83, v83, 16, v84
	v_add_u32_e32 v84, s98, v174
	ds_write_b128 v84, v[80:83]
.LBB0_408:
	s_or_b64 exec, exec, vcc
	s_branch .LBB0_398
.LBB0_414:
	v_subrev_u32_e32 v147, s98, v147
	v_subrev_u32_e32 v148, s98, v148
	v_subrev_u32_e32 v149, s98, v149
	v_subrev_u32_e32 v150, s98, v150
	v_subrev_u32_e32 v151, s98, v151
	v_subrev_u32_e32 v152, s98, v152
	v_subrev_u32_e32 v153, s98, v153
	v_subrev_u32_e32 v154, s98, v154
	v_subrev_u32_e32 v141, s99, v141
	v_subrev_u32_e32 v175, s99, v175
	v_subrev_u32_e32 v178, s99, v178
	v_subrev_u32_e32 v179, s99, v179
	s_and_b64 vcc, exec, s[14:15]
	s_cbranch_vccz .LBB0_394
	v_cndmask_b32_e64 v0, v144, v143, s[76:77]
	v_mov_b32_e32 v1, v177
	v_add_u32_e32 v6, s7, v129
	v_add_u32_e32 v6, s98, v6
	v_lshl_add_u64 v[0:1], s[82:83], 0, v[0:1]
	ds_read2st64_b32 v[2:3], v6 offset1:1
	ds_read2st64_b32 v[4:5], v6 offset0:2 offset1:3
	v_lshlrev_b64 v[0:1], 12, v[0:1]
	v_lshl_add_u64 v[0:1], s[16:17], 0, v[0:1]
	v_lshl_add_u64 v[0:1], v[0:1], 0, s[80:81]
	s_mov_b32 s3, s81
	v_lshl_add_u64 v[0:1], v[0:1], 0, s[2:3]
	v_lshl_add_u64 v[0:1], s[8:9], 1, v[0:1]
	v_mov_b32_e32 v125, v177
	s_waitcnt lgkmcnt(1)
	v_pk_add_f32 v[2:3], v[64:65], v[2:3]
	s_waitcnt lgkmcnt(0)
	v_pk_add_f32 v[4:5], v[66:67], v[4:5]
	v_lshl_add_u64 v[0:1], v[0:1], 0, v[124:125]
	v_cvt_pk_bf16_f32 v2, v2, v3
	v_cvt_pk_bf16_f32 v3, v4, v5
	global_store_dwordx2 v[0:1], v[2:3], off
	ds_read2st64_b32 v[2:3], v6 offset0:4 offset1:5
	ds_read2st64_b32 v[4:5], v6 offset0:6 offset1:7
	s_waitcnt lgkmcnt(1)
	v_pk_add_f32 v[2:3], v[68:69], v[2:3]
	s_waitcnt lgkmcnt(0)
	v_pk_add_f32 v[4:5], v[70:71], v[4:5]
	v_cvt_pk_bf16_f32 v2, v2, v3
	v_cvt_pk_bf16_f32 v3, v4, v5
	global_store_dwordx2 v[0:1], v[2:3], off offset:16
	ds_read2st64_b32 v[2:3], v6 offset0:8 offset1:9
	ds_read2st64_b32 v[4:5], v6 offset0:10 offset1:11
	s_waitcnt lgkmcnt(1)
	v_pk_add_f32 v[2:3], v[72:73], v[2:3]
	s_waitcnt lgkmcnt(0)
	v_pk_add_f32 v[4:5], v[74:75], v[4:5]
	v_cvt_pk_bf16_f32 v2, v2, v3
	v_cvt_pk_bf16_f32 v3, v4, v5
	global_store_dwordx2 v[0:1], v[2:3], off offset:32
	ds_read2st64_b32 v[2:3], v6 offset0:12 offset1:13
	ds_read2st64_b32 v[4:5], v6 offset0:14 offset1:15
	s_waitcnt lgkmcnt(1)
	v_pk_add_f32 v[2:3], v[76:77], v[2:3]
	s_waitcnt lgkmcnt(0)
	v_pk_add_f32 v[4:5], v[78:79], v[4:5]
	v_cvt_pk_bf16_f32 v2, v2, v3
	v_cvt_pk_bf16_f32 v3, v4, v5
	global_store_dwordx2 v[0:1], v[2:3], off offset:48
	s_branch .LBB0_394

	.amdhsa_kernel _Z14fwd_megakernel6Params
		.amdhsa_group_segment_fixed_size 147472
		.amdhsa_private_segment_fixed_size 0
		.amdhsa_kernarg_size 432
		.amdhsa_user_sgpr_count 2
		.amdhsa_user_sgpr_dispatch_ptr 0
		.amdhsa_user_sgpr_queue_ptr 0
		.amdhsa_user_sgpr_kernarg_segment_ptr 1
		.amdhsa_user_sgpr_dispatch_id 0
		.amdhsa_user_sgpr_kernarg_preload_length 0
		.amdhsa_user_sgpr_kernarg_preload_offset 0
		.amdhsa_user_sgpr_private_segment_size 0
		.amdhsa_uses_dynamic_stack 0
		.amdhsa_enable_private_segment 0
		.amdhsa_system_sgpr_workgroup_id_x 1
		.amdhsa_system_sgpr_workgroup_id_y 0
		.amdhsa_system_sgpr_workgroup_id_z 0
		.amdhsa_system_sgpr_workgroup_info 0
		.amdhsa_system_vgpr_workitem_id 2
		.amdhsa_next_free_vgpr 254
		.amdhsa_next_free_sgpr 101
		.amdhsa_accum_offset 256
		.amdhsa_reserve_vcc 1
		.amdhsa_float_round_mode_32 0
		.amdhsa_float_round_mode_16_64 0
		.amdhsa_float_denorm_mode_32 3
		.amdhsa_float_denorm_mode_16_64 3
		.amdhsa_dx10_clamp 1
		.amdhsa_ieee_mode 1
		.amdhsa_fp16_overflow 0
		.amdhsa_tg_split 0
		.amdhsa_exception_fp_ieee_invalid_op 0
		.amdhsa_exception_fp_denorm_src 0
		.amdhsa_exception_fp_ieee_div_zero 0
		.amdhsa_exception_fp_ieee_overflow 0
		.amdhsa_exception_fp_ieee_underflow 0
		.amdhsa_exception_fp_ieee_inexact 0
		.amdhsa_exception_int_div_zero 0
	.end_amdhsa_kernel

amdhsa.kernels:
  - .agpr_count:     0
    .args:
      - .offset:         0
        .size:           176
        .value_kind:     by_value
      - .offset:         176
        .size:           4
        .value_kind:     hidden_block_count_x
      - .offset:         180
        .size:           4
        .value_kind:     hidden_block_count_y
      - .offset:         184
        .size:           4
        .value_kind:     hidden_block_count_z
      - .offset:         188
        .size:           2
        .value_kind:     hidden_group_size_x
      - .offset:         190
        .size:           2
        .value_kind:     hidden_group_size_y
      - .offset:         192
        .size:           2
        .value_kind:     hidden_group_size_z
      - .offset:         194
        .size:           2
        .value_kind:     hidden_remainder_x
      - .offset:         196
        .size:           2
        .value_kind:     hidden_remainder_y
      - .offset:         198
        .size:           2
        .value_kind:     hidden_remainder_z
      - .offset:         216
        .size:           8
        .value_kind:     hidden_global_offset_x
      - .offset:         224
        .size:           8
        .value_kind:     hidden_global_offset_y
      - .offset:         232
        .size:           8
        .value_kind:     hidden_global_offset_z
      - .offset:         240
        .size:           2
        .value_kind:     hidden_grid_dims
      - .offset:         264
        .size:           8
        .value_kind:     hidden_multigrid_sync_arg
    .group_segment_fixed_size: 147472
    .kernarg_segment_align: 8
    .kernarg_segment_size: 432
    .language:       OpenCL C
    .language_version:
      - 2
      - 0
    .max_flat_workgroup_size: 512
    .name:           _Z14fwd_megakernel6Params
    .private_segment_fixed_size: 0
    .sgpr_count:     107
    .sgpr_spill_count: 191
    .symbol:         _Z14fwd_megakernel6Params.kd
    .uniform_work_group_size: 1
    .uses_dynamic_stack: false
    .vgpr_count:     254
    .vgpr_spill_count: 0
    .wavefront_size: 64
